# pk1
# baseline (speedup 1.0000x reference)
; template <int EPI>
; __device__ __forceinline__ void gemm_phase(const GemmDesc d, u16* shm, unsigned sx, unsigned srank, unsigned snloc) {
;     ...
;       float ssn = 0.f;
;       if constexpr (NEED_R) {
;         if (has_next && t2 < 256) ssn = SS_ROW(d.ss + (size_t)R_ROW(pmn, pnn, t2) * 16);
;       }
;       float* stg = (float*)((char*)shm + GEMM_LDS + 2048 + wid2 * 2304);
;       const float* lr = lds_r + (it & 1) * 256;
;       const int rl = lane2 >> 3, c4 = (lane2 & 7) * 4;
;       if constexpr (EPI == E_SWIGLU) {
;         using f32x2 = __attribute__((ext_vector_type(2))) float;
;         const int sw_row = lane2 >> 2, sw_c8 = (lane2 & 3) * 8;
;         u16* sw_base = d.outb + ((size_t)(brow >> 7) * 44 + pn * 2 + (wc2 >> 1)) * 8192
;                      + ((((sw_row * 64 + sw_c8 * 2) ^ ((sw_row >> 3) << 5)) + (wr2 * 8 + (wc2 & 1)) * 1024) >> 1);
; #pragma unroll
;         for (int ai = 0; ai < 2; ++ai)
; #pragma unroll
;           for (int m = 0; m < 4; ++m) {
;             const f32x4 r4 = *(const f32x4*)&lr[ai * 128 + wr2 * 64 + m * 16 + fq2 * 4];
;             const f32x4 rc4 = r4 * (-1.4426950408889634f), rr4 = r4 * r4;
; #pragma unroll
;             for (int n = 0; n < 2; ++n)
; #pragma unroll
;               for (int jp = 0; jp < 4; jp += 2) {
;                 const f32x2 a = {acc[ai][0][m][n][jp], acc[ai][0][m][n][jp + 1]}, b = {acc[ai][1][m][n][jp], acc[ai][1][m][n][jp + 1]};
;                 const f32x2 rc = {rc4[jp], rc4[jp + 1]}, rr = {rr4[jp], rr4[jp + 1]};
;                 const f32x2 tl = a * rc;
;                 f32x2 dd = {__builtin_amdgcn_exp2f(tl[0]), __builtin_amdgcn_exp2f(tl[1])};
;                 dd = dd + 1.0f;
;                 const f32x2 s = {__builtin_amdgcn_rcpf(dd[0]), __builtin_amdgcn_rcpf(dd[1])};
;                 const f32x2 o = (a * b) * (rr * s);
;                 stg[(fq2 * 4 + jp) * 36 + n * 16 + fr2] = o[0];
;                 stg[(fq2 * 4 + jp + 1) * 36 + n * 16 + fr2] = o[1];
;               }
;             {
;               const f32x4 v0 = *(const f32x4*)&stg[sw_row * 36 + sw_c8], v1 = *(const f32x4*)&stg[sw_row * 36 + sw_c8 + 4];
;               u32x4 w = {pack2(v0[0], v0[1]), pack2(v0[2], v0[3]), pack2(v1[0], v1[1]), pack2(v1[2], v1[3])};
;               __builtin_nontemporal_store(w, (u32x4*)(sw_base + (size_t)ai * (44 * 8192) + m * 1024));
;             }
.LBB0_1450:
	s_or_b64 exec, exec, s[4:5]
	v_mov_b32_e32 v139, v182
	v_mov_b32_e32 v140, 0x358637bd
	v_cmp_gt_i32_e32 vcc, s58, v139
	s_and_b64 s[34:35], s[26:27], vcc
	s_and_saveexec_b64 s[4:5], s[34:35]
	s_mov_b32 s31, 0x800000
	s_movk_i32 s28, 0x1000
	s_cbranch_execz .LBB0_1452
	v_lshl_add_u32 v128, s85, 8, v139
	v_ashrrev_i32_e32 v129, 31, v128
	v_lshlrev_b64 v[128:129], 6, v[128:129]
	v_lshl_add_u64 v[128:129], s[10:11], 0, v[128:129]
	global_load_dwordx4 v[140:143], v[128:129], off
	global_load_dwordx4 v[144:147], v[128:129], off offset:16
	global_load_dwordx4 v[148:151], v[128:129], off offset:32
	global_load_dwordx4 v[152:155], v[128:129], off offset:48
	s_waitcnt vmcnt(3)
	v_mov_b32_e32 v128, v140
	s_waitcnt vmcnt(2)
	v_mov_b32_e32 v129, v144
	v_mov_b32_e32 v144, v141
	v_mov_b32_e32 v140, v142
	v_mov_b32_e32 v141, v146
	v_mov_b32_e32 v146, v143
	s_waitcnt vmcnt(1)
	v_mov_b32_e32 v142, v148
	s_waitcnt vmcnt(0)
	v_mov_b32_e32 v143, v152
	v_mov_b32_e32 v152, v149
	v_add_f32_e32 v128, v128, v144
	v_add_f32_e32 v129, v129, v145
	v_mov_b32_e32 v148, v150
	v_mov_b32_e32 v149, v154
	v_add_f32_e32 v142, v142, v152
	v_add_f32_e32 v143, v143, v153
	v_add_f32_e32 v128, v140, v128
	v_add_f32_e32 v129, v141, v129
	v_mov_b32_e32 v154, v151
	v_add_f32_e32 v140, v148, v142
	v_add_f32_e32 v141, v149, v143
	v_add_f32_e32 v128, v146, v128
	v_add_f32_e32 v129, v147, v129
	v_add_f32_e32 v140, v154, v140
	v_add_f32_e32 v141, v155, v141
	v_add_f32_e32 v128, v128, v129
	v_add_f32_e32 v128, v128, v140
	v_add_f32_e32 v128, v128, v141
	v_fmamk_f32 v140, v128, 0x3a800000, v186
.LBB0_1452:
	s_or_b64 exec, exec, s[4:5]
	v_ashrrev_i32_e32 v141, 6, v139
	s_movk_i32 s0, 0x900
	v_mul_lo_u32 v128, v141, s0
	s_lshl_b32 s0, s70, 8
	s_and_b32 s18, s0, 0x100
	v_add_u32_e32 v156, s83, v128
	s_lshl_b32 s0, s18, 2
	v_lshlrev_b32_e32 v128, 3, v139
	s_add_i32 s0, s0, 0
	v_bfe_u32 v145, v139, 2, 4
	v_and_b32_e32 v146, 24, v128
	s_lshl_b32 s5, s88, 1
	s_add_i32 s0, s0, 0x20000
	s_lshl_b32 s1, s89, 1
	s_mul_i32 s4, s89, 0x58
	s_ashr_i32 s19, s5, 31
	v_lshlrev_b32_e32 v142, 6, v145
	v_lshlrev_b32_e32 v143, 1, v146
	v_and_b32_e32 v147, 32, v139
	s_mul_hi_i32 s1, s1, 44
	s_add_u32 s4, s4, s5
	v_lshrrev_b32_e32 v128, 1, v141
	v_bitop3_b32 v142, v142, v147, v143 bitop3:0x36
	v_lshlrev_b32_e32 v143, 5, v139
	v_lshlrev_b32_e32 v141, 10, v141
	s_addc_u32 s1, s1, s19
	v_and_b32_e32 v143, 0xffffe000, v143
	v_and_b32_e32 v141, 0x400, v141
	v_and_or_b32 v128, v128, 1, s4
	v_mov_b32_e32 v129, s1
	v_or3_b32 v141, v141, v143, v142
	v_lshlrev_b64 v[128:129], 14, v[128:129]
	v_ashrrev_i32_e32 v142, 1, v141
	v_lshrrev_b32_e32 v144, 2, v139
	v_lshl_add_u64 v[128:129], s[12:13], 0, v[128:129]
	v_ashrrev_i32_e32 v143, 31, v142
	v_lshl_add_u64 v[128:129], v[142:143], 1, v[128:129]
	v_and_b32_e32 v143, 12, v144
	v_and_b32_e32 v141, 0xffffff00, v139
	v_lshlrev_b32_e32 v142, 2, v143
	v_add3_u32 v142, s0, v141, v142
	v_lshlrev_b32_e32 v141, 2, v139
	v_and_b32_e32 v157, 60, v141
	v_mul_u32_u24_e32 v141, 0x90, v145
	v_lshlrev_b32_e32 v144, 2, v146
	v_add3_u32 v141, v156, v141, v144
	ds_read_b128 v[144:147], v142
	v_mul_f32_e32 v122, v126, v122
	v_mul_f32_e32 v123, v127, v123
	v_mul_f32_e32 v120, v124, v120
	v_mul_f32_e32 v121, v125, v121
	v_mul_f32_e32 v112, v116, v112
	v_mul_f32_e32 v113, v117, v113
	v_mul_f32_e32 v114, v118, v114
	v_mul_f32_e32 v115, v119, v115
	s_waitcnt lgkmcnt(0)
	v_mul_f32_e32 v148, s86, v146
	v_mul_f32_e32 v149, s86, v147
	v_mul_f32_e32 v150, s86, v144
	v_mul_f32_e32 v151, s86, v145
	v_mul_f32_e32 v152, v126, v148
	v_mul_f32_e32 v153, v127, v149
	v_mul_f32_e32 v146, v146, v146
	v_mul_f32_e32 v147, v147, v147
	v_exp_f32_e32 v126, v152
	v_exp_f32_e32 v127, v153
	v_mul_f32_e32 v154, v124, v150
	v_mul_f32_e32 v155, v125, v151
	v_mul_f32_e32 v144, v144, v144
	v_mul_f32_e32 v145, v145, v145
	v_exp_f32_e32 v154, v154
	v_add_f32_e32 v126, 1.0, v126
	v_add_f32_e32 v127, 1.0, v127
	v_exp_f32_e32 v155, v155
	v_rcp_f32_e32 v126, v126
	v_rcp_f32_e32 v127, v127
	v_mul_f32_e32 v106, v110, v106
	v_mul_f32_e32 v107, v111, v107
	v_add_f32_e32 v154, 1.0, v154
	v_add_f32_e32 v155, 1.0, v155
	v_mul_f32_e32 v104, v108, v104
	v_mul_f32_e32 v105, v109, v105
	v_mul_f32_e32 v126, v146, v126
	v_mul_f32_e32 v127, v147, v127
	v_rcp_f32_e32 v154, v154
	v_mul_f32_e32 v122, v122, v126
	v_mul_f32_e32 v123, v123, v127
	v_mul_f32_e32 v126, v118, v148
	v_mul_f32_e32 v127, v119, v149
	v_mul_f32_e32 v148, v116, v150
	v_mul_f32_e32 v149, v117, v151
	v_rcp_f32_e32 v155, v155
	v_exp_f32_e32 v148, v148
	v_exp_f32_e32 v149, v149
	v_mul_f32_e32 v96, v100, v96
	v_mul_f32_e32 v97, v101, v97
	v_mul_f32_e32 v124, v144, v154
	v_mul_f32_e32 v125, v145, v155
	v_mul_f32_e32 v98, v102, v98
	v_mul_f32_e32 v99, v103, v99
	v_add_f32_e32 v148, 1.0, v148
	v_add_f32_e32 v149, 1.0, v149
	v_mul_f32_e32 v124, v120, v124
	v_mul_f32_e32 v125, v121, v125
	v_rcp_f32_e32 v148, v148
	v_rcp_f32_e32 v149, v149
	v_mul_u32_u24_e32 v120, 36, v143
	v_lshlrev_b32_e32 v121, 2, v120
	v_add3_u32 v120, v156, v157, v121
	v_mul_f32_e32 v116, v144, v148
	v_mul_f32_e32 v117, v145, v149
	v_add3_u32 v121, v156, v121, v157
	v_mul_f32_e32 v112, v112, v116
	v_mul_f32_e32 v113, v113, v117
	ds_write2_b32 v120, v124, v112 offset1:16
	ds_write2_b32 v121, v125, v113 offset0:36 offset1:52
	v_exp_f32_e32 v112, v126
	v_exp_f32_e32 v113, v127
	v_mul_f32_e32 v90, v94, v90
	v_mul_f32_e32 v91, v95, v91
	v_mul_f32_e32 v88, v92, v88
	v_mul_f32_e32 v89, v93, v89
	v_mul_f32_e32 v80, v84, v80
	v_mul_f32_e32 v81, v85, v81
	v_add_f32_e32 v112, 1.0, v112
	v_add_f32_e32 v113, 1.0, v113
	v_mul_f32_e32 v82, v86, v82
	v_mul_f32_e32 v83, v87, v83
	v_rcp_f32_e32 v112, v112
	v_rcp_f32_e32 v113, v113
	v_mul_f32_e32 v74, v78, v74
	v_mul_f32_e32 v75, v79, v75
	v_mul_f32_e32 v72, v76, v72
	v_mul_f32_e32 v73, v77, v73
	v_mul_f32_e32 v64, v68, v64
	v_mul_f32_e32 v65, v69, v65
	v_mul_f32_e32 v112, v146, v112
	v_mul_f32_e32 v113, v147, v113
	v_mul_f32_e32 v66, v70, v66
	v_mul_f32_e32 v67, v71, v67
	v_mul_f32_e32 v112, v114, v112
	v_mul_f32_e32 v113, v115, v113
	ds_write2_b32 v120, v122, v112 offset0:72 offset1:88
	ds_write2_b32 v121, v123, v113 offset0:108 offset1:124
	ds_read_b128 v[112:115], v141
	ds_read_b128 v[116:119], v141 offset:16
	s_waitcnt lgkmcnt(1)
; __device__ __forceinline__ unsigned pack2(float lo, float hi) { unsigned r; asm volatile("v_cvt_pk_bf16_f32 %0, %1, %2" : "=v"(r) : "v"(lo), "v"(hi)); return r; }
; template <int EPI>
; __device__ __forceinline__ void gemm_phase(const GemmDesc d, u16* shm, unsigned sx, unsigned srank, unsigned snloc) {
;     ...
;             const f32x4 r4 = *(const f32x4*)&lr[ai * 128 + wr2 * 64 + m * 16 + fq2 * 4];
;             const f32x4 rc4 = r4 * (-1.4426950408889634f), rr4 = r4 * r4;
; #pragma unroll
;             for (int n = 0; n < 2; ++n)
; #pragma unroll
;               for (int jp = 0; jp < 4; jp += 2) {
;                 const f32x2 a = {acc[ai][0][m][n][jp], acc[ai][0][m][n][jp + 1]}, b = {acc[ai][1][m][n][jp], acc[ai][1][m][n][jp + 1]};
;                 const f32x2 rc = {rc4[jp], rc4[jp + 1]}, rr = {rr4[jp], rr4[jp + 1]};
;                 const f32x2 tl = a * rc;
;                 f32x2 dd = {__builtin_amdgcn_exp2f(tl[0]), __builtin_amdgcn_exp2f(tl[1])};
;                 dd = dd + 1.0f;
;                 const f32x2 s = {__builtin_amdgcn_rcpf(dd[0]), __builtin_amdgcn_rcpf(dd[1])};
;                 const f32x2 o = (a * b) * (rr * s);
;                 stg[(fq2 * 4 + jp) * 36 + n * 16 + fr2] = o[0];
;                 stg[(fq2 * 4 + jp + 1) * 36 + n * 16 + fr2] = o[1];
;               }
;             {
;               const f32x4 v0 = *(const f32x4*)&stg[sw_row * 36 + sw_c8], v1 = *(const f32x4*)&stg[sw_row * 36 + sw_c8 + 4];
;               u32x4 w = {pack2(v0[0], v0[1]), pack2(v0[2], v0[3]), pack2(v1[0], v1[1]), pack2(v1[2], v1[3])};
;               __builtin_nontemporal_store(w, (u32x4*)(sw_base + (size_t)ai * (44 * 8192) + m * 1024));
;             }
	v_cvt_pk_bf16_f32 v112, v112, v113
	v_cvt_pk_bf16_f32 v113, v114, v115
	s_waitcnt lgkmcnt(0)
	v_cvt_pk_bf16_f32 v114, v116, v117
	v_cvt_pk_bf16_f32 v115, v118, v119
	global_store_dwordx4 v[128:129], v[112:115], off nt
	ds_read_b128 v[112:115], v142 offset:64
	v_mul_f32_e32 v58, v62, v58
	v_mul_f32_e32 v59, v63, v59
	v_mul_f32_e32 v56, v60, v56
	v_mul_f32_e32 v57, v61, v57
	v_mul_f32_e32 v48, v52, v48
	v_mul_f32_e32 v49, v53, v49
	v_mul_f32_e32 v50, v54, v50
	v_mul_f32_e32 v51, v55, v51
	s_waitcnt lgkmcnt(0)
	v_mul_f32_e32 v118, s86, v112
	v_mul_f32_e32 v119, s86, v113
	v_mul_f32_e32 v116, s86, v114
	v_mul_f32_e32 v117, s86, v115
	v_mul_f32_e32 v124, v108, v118
	v_mul_f32_e32 v125, v109, v119
	v_mul_f32_e32 v112, v112, v112
	v_mul_f32_e32 v113, v113, v113
	v_exp_f32_e32 v124, v124
	v_exp_f32_e32 v125, v125
	v_mul_f32_e32 v122, v110, v116
	v_mul_f32_e32 v123, v111, v117
	v_mul_f32_e32 v110, v100, v118
	v_mul_f32_e32 v111, v101, v119
	v_mul_f32_e32 v114, v114, v114
	v_mul_f32_e32 v115, v115, v115
	v_add_f32_e32 v124, 1.0, v124
	v_add_f32_e32 v125, 1.0, v125
	v_exp_f32_e32 v110, v110
	v_rcp_f32_e32 v124, v124
	v_rcp_f32_e32 v125, v125
	v_exp_f32_e32 v111, v111
	s_mov_b32 s0, 0xb0000
	v_mul_f32_e32 v42, v46, v42
	v_mul_f32_e32 v43, v47, v43
	v_mul_f32_e32 v108, v112, v124
	v_mul_f32_e32 v109, v113, v125
	v_add_f32_e32 v110, 1.0, v110
	v_add_f32_e32 v111, 1.0, v111
	v_mul_f32_e32 v104, v104, v108
	v_mul_f32_e32 v105, v105, v109
	v_exp_f32_e32 v108, v122
	v_exp_f32_e32 v109, v123
	v_rcp_f32_e32 v110, v110
	v_rcp_f32_e32 v111, v111
	v_mul_f32_e32 v40, v44, v40
	v_mul_f32_e32 v41, v45, v41
	v_add_f32_e32 v108, 1.0, v108
	v_add_f32_e32 v109, 1.0, v109
	v_mul_f32_e32 v32, v36, v32
	v_mul_f32_e32 v33, v37, v33
	v_rcp_f32_e32 v108, v108
	v_rcp_f32_e32 v109, v109
	v_mul_f32_e32 v100, v112, v110
	v_mul_f32_e32 v101, v113, v111
	v_mul_f32_e32 v34, v38, v34
	v_mul_f32_e32 v35, v39, v35
	v_mul_f32_e32 v96, v96, v100
	v_mul_f32_e32 v97, v97, v101
	v_mul_f32_e32 v108, v114, v108
	v_mul_f32_e32 v109, v115, v109
	ds_write2_b32 v120, v104, v96 offset1:16
	ds_write2_b32 v121, v105, v97 offset0:36 offset1:52
	v_mul_f32_e32 v106, v106, v108
	v_mul_f32_e32 v107, v107, v109
	v_mul_f32_e32 v108, v102, v116
	v_mul_f32_e32 v109, v103, v117
	v_mul_f32_e32 v26, v30, v26
	v_mul_f32_e32 v27, v31, v27
	v_exp_f32_e32 v96, v108
	v_exp_f32_e32 v97, v109
	v_mul_f32_e32 v24, v28, v24
	v_mul_f32_e32 v25, v29, v25
	v_mul_f32_e32 v16, v20, v16
	v_mul_f32_e32 v17, v21, v17
	v_mul_f32_e32 v18, v22, v18
	v_mul_f32_e32 v19, v23, v19
	v_add_f32_e32 v96, 1.0, v96
	v_add_f32_e32 v97, 1.0, v97
	v_mul_f32_e32 v10, v14, v10
	v_mul_f32_e32 v11, v15, v11
	v_rcp_f32_e32 v96, v96
	v_rcp_f32_e32 v97, v97
	v_mul_f32_e32 v8, v12, v8
	v_mul_f32_e32 v9, v13, v9
	v_mul_f32_e32 v0, v4, v0
	v_mul_f32_e32 v1, v5, v1
	v_mul_f32_e32 v2, v6, v2
	v_mul_f32_e32 v3, v7, v3
	v_mul_f32_e32 v96, v114, v96
	v_mul_f32_e32 v97, v115, v97
	s_nop 0
	v_mul_f32_e32 v96, v98, v96
	v_mul_f32_e32 v97, v99, v97
	ds_write2_b32 v120, v106, v96 offset0:72 offset1:88
	ds_write2_b32 v121, v107, v97 offset0:108 offset1:124
	ds_read_b128 v[96:99], v141
	ds_read_b128 v[100:103], v141 offset:16
	s_waitcnt lgkmcnt(1)
	v_cvt_pk_bf16_f32 v96, v96, v97
	v_cvt_pk_bf16_f32 v97, v98, v99
	s_waitcnt lgkmcnt(0)
	v_cvt_pk_bf16_f32 v98, v100, v101
	v_cvt_pk_bf16_f32 v99, v102, v103
	global_store_dwordx4 v[128:129], v[96:99], off offset:2048 nt
	ds_read_b128 v[96:99], v142 offset:128
	s_waitcnt lgkmcnt(0)
	v_mul_f32_e32 v102, s86, v96
	v_mul_f32_e32 v103, s86, v97
	s_nop 0
	v_mul_f32_e32 v106, v92, v102
	v_mul_f32_e32 v107, v93, v103
	v_mul_f32_e32 v100, s86, v98
	v_mul_f32_e32 v101, s86, v99
	v_exp_f32_e32 v106, v106
	v_exp_f32_e32 v107, v107
	v_mul_f32_e32 v96, v96, v96
	v_mul_f32_e32 v97, v97, v97
	v_mul_f32_e32 v104, v94, v100
	v_mul_f32_e32 v105, v95, v101
	v_mul_f32_e32 v94, v84, v102
	v_mul_f32_e32 v95, v85, v103
	v_add_f32_e32 v106, 1.0, v106
	v_add_f32_e32 v107, 1.0, v107
	v_exp_f32_e32 v94, v94
	v_rcp_f32_e32 v106, v106
	v_rcp_f32_e32 v107, v107
	v_exp_f32_e32 v95, v95
	v_mul_f32_e32 v98, v98, v98
	v_mul_f32_e32 v99, v99, v99
	v_mul_f32_e32 v92, v96, v106
	v_mul_f32_e32 v93, v97, v107
	s_nop 0
	v_mul_f32_e32 v88, v88, v92
	v_mul_f32_e32 v89, v89, v93
	v_exp_f32_e32 v92, v104
	v_exp_f32_e32 v93, v105
	v_add_f32_e32 v94, 1.0, v94
	v_add_f32_e32 v95, 1.0, v95
	v_add_f32_e32 v92, 1.0, v92
	v_add_f32_e32 v93, 1.0, v93
	s_nop 0
	v_rcp_f32_e32 v92, v92
	v_rcp_f32_e32 v93, v93
	v_rcp_f32_e32 v94, v94
	v_rcp_f32_e32 v95, v95
	v_mul_f32_e32 v92, v98, v92
	v_mul_f32_e32 v93, v99, v93
	s_nop 0
	v_mul_f32_e32 v90, v90, v92
	v_mul_f32_e32 v91, v91, v93
	v_mul_f32_e32 v84, v96, v94
	v_mul_f32_e32 v85, v97, v95
	v_mul_f32_e32 v92, v86, v100
	v_mul_f32_e32 v93, v87, v101
	v_mul_f32_e32 v80, v80, v84
	v_mul_f32_e32 v81, v81, v85
	ds_write2_b32 v120, v88, v80 offset1:16
	ds_write2_b32 v121, v89, v81 offset0:36 offset1:52
	v_exp_f32_e32 v80, v92
	v_exp_f32_e32 v81, v93
	s_nop 0
	v_add_f32_e32 v80, 1.0, v80
	v_add_f32_e32 v81, 1.0, v81
	s_nop 0
	v_rcp_f32_e32 v80, v80
	v_rcp_f32_e32 v81, v81
	s_nop 0
	v_mul_f32_e32 v80, v98, v80
	v_mul_f32_e32 v81, v99, v81
	s_nop 0
	v_mul_f32_e32 v80, v82, v80
	v_mul_f32_e32 v81, v83, v81
	ds_write2_b32 v120, v90, v80 offset0:72 offset1:88
	ds_write2_b32 v121, v91, v81 offset0:108 offset1:124
	ds_read_b128 v[80:83], v141
	ds_read_b128 v[84:87], v141 offset:16
	s_waitcnt lgkmcnt(1)
	v_cvt_pk_bf16_f32 v80, v80, v81
	v_cvt_pk_bf16_f32 v81, v82, v83
	s_waitcnt lgkmcnt(0)
	v_cvt_pk_bf16_f32 v82, v84, v85
	v_add_co_u32_e32 v84, vcc, s28, v128
	v_cvt_pk_bf16_f32 v83, v86, v87
	s_nop 1
	v_addc_co_u32_e32 v85, vcc, 0, v129, vcc
	global_store_dwordx4 v[84:85], v[80:83], off nt
	ds_read_b128 v[80:83], v142 offset:192
	s_waitcnt lgkmcnt(0)
; __device__ __forceinline__ unsigned pack2(float lo, float hi) { unsigned r; asm volatile("v_cvt_pk_bf16_f32 %0, %1, %2" : "=v"(r) : "v"(lo), "v"(hi)); return r; }
; template <int EPI>
; __device__ __forceinline__ void gemm_phase(const GemmDesc d, u16* shm, unsigned sx, unsigned srank, unsigned snloc) {
;     ...
;             const f32x4 r4 = *(const f32x4*)&lr[ai * 128 + wr2 * 64 + m * 16 + fq2 * 4];
;             const f32x4 rc4 = r4 * (-1.4426950408889634f), rr4 = r4 * r4;
; #pragma unroll
;             for (int n = 0; n < 2; ++n)
; #pragma unroll
;               for (int jp = 0; jp < 4; jp += 2) {
;                 const f32x2 a = {acc[ai][0][m][n][jp], acc[ai][0][m][n][jp + 1]}, b = {acc[ai][1][m][n][jp], acc[ai][1][m][n][jp + 1]};
;                 const f32x2 rc = {rc4[jp], rc4[jp + 1]}, rr = {rr4[jp], rr4[jp + 1]};
;                 const f32x2 tl = a * rc;
;                 f32x2 dd = {__builtin_amdgcn_exp2f(tl[0]), __builtin_amdgcn_exp2f(tl[1])};
;                 dd = dd + 1.0f;
;                 const f32x2 s = {__builtin_amdgcn_rcpf(dd[0]), __builtin_amdgcn_rcpf(dd[1])};
;                 const f32x2 o = (a * b) * (rr * s);
;                 stg[(fq2 * 4 + jp) * 36 + n * 16 + fr2] = o[0];
;                 stg[(fq2 * 4 + jp + 1) * 36 + n * 16 + fr2] = o[1];
;               }
;             {
;               const f32x4 v0 = *(const f32x4*)&stg[sw_row * 36 + sw_c8], v1 = *(const f32x4*)&stg[sw_row * 36 + sw_c8 + 4];
;               u32x4 w = {pack2(v0[0], v0[1]), pack2(v0[2], v0[3]), pack2(v1[0], v1[1]), pack2(v1[2], v1[3])};
;               __builtin_nontemporal_store(w, (u32x4*)(sw_base + (size_t)ai * (44 * 8192) + m * 1024));
;             }
	v_mul_f32_e32 v88, s86, v80
	v_mul_f32_e32 v89, s86, v81
	s_nop 0
	v_mul_f32_e32 v92, v76, v88
	v_mul_f32_e32 v93, v77, v89
	v_mul_f32_e32 v86, s86, v82
	v_mul_f32_e32 v87, s86, v83
	v_exp_f32_e32 v92, v92
	v_exp_f32_e32 v93, v93
	v_mul_f32_e32 v80, v80, v80
	v_mul_f32_e32 v81, v81, v81
	v_mul_f32_e32 v90, v78, v86
	v_mul_f32_e32 v91, v79, v87
	v_mul_f32_e32 v78, v68, v88
	v_mul_f32_e32 v79, v69, v89
	v_add_f32_e32 v92, 1.0, v92
	v_add_f32_e32 v93, 1.0, v93
	v_exp_f32_e32 v78, v78
	v_rcp_f32_e32 v92, v92
	v_rcp_f32_e32 v93, v93
	v_exp_f32_e32 v79, v79
	v_mul_f32_e32 v82, v82, v82
	v_mul_f32_e32 v83, v83, v83
	v_mul_f32_e32 v76, v80, v92
	v_mul_f32_e32 v77, v81, v93
	s_nop 0
	v_mul_f32_e32 v72, v72, v76
	v_mul_f32_e32 v73, v73, v77
	v_exp_f32_e32 v76, v90
	v_exp_f32_e32 v77, v91
	v_add_f32_e32 v78, 1.0, v78
	v_add_f32_e32 v79, 1.0, v79
	v_add_f32_e32 v76, 1.0, v76
	v_add_f32_e32 v77, 1.0, v77
	s_nop 0
	v_rcp_f32_e32 v76, v76
	v_rcp_f32_e32 v77, v77
	v_rcp_f32_e32 v78, v78
	v_rcp_f32_e32 v79, v79
	v_mul_f32_e32 v76, v82, v76
	v_mul_f32_e32 v77, v83, v77
	s_nop 0
	v_mul_f32_e32 v74, v74, v76
	v_mul_f32_e32 v75, v75, v77
	v_mul_f32_e32 v68, v80, v78
	v_mul_f32_e32 v69, v81, v79
	v_mul_f32_e32 v76, v70, v86
	v_mul_f32_e32 v77, v71, v87
	v_mul_f32_e32 v64, v64, v68
	v_mul_f32_e32 v65, v65, v69
	ds_write2_b32 v120, v72, v64 offset1:16
	ds_write2_b32 v121, v73, v65 offset0:36 offset1:52
	v_exp_f32_e32 v64, v76
	v_exp_f32_e32 v65, v77
	s_nop 0
	v_add_f32_e32 v64, 1.0, v64
	v_add_f32_e32 v65, 1.0, v65
	s_nop 0
	v_rcp_f32_e32 v64, v64
	v_rcp_f32_e32 v65, v65
	s_nop 0
	v_mul_f32_e32 v64, v82, v64
	v_mul_f32_e32 v65, v83, v65
	s_nop 0
	v_mul_f32_e32 v64, v66, v64
	v_mul_f32_e32 v65, v67, v65
	ds_write2_b32 v120, v74, v64 offset0:72 offset1:88
	ds_write2_b32 v121, v75, v65 offset0:108 offset1:124
	ds_read_b128 v[64:67], v141
	ds_read_b128 v[68:71], v141 offset:16
	s_waitcnt lgkmcnt(1)
	v_cvt_pk_bf16_f32 v64, v64, v65
	v_cvt_pk_bf16_f32 v65, v66, v67
	s_waitcnt lgkmcnt(0)
	v_cvt_pk_bf16_f32 v66, v68, v69
	v_cvt_pk_bf16_f32 v67, v70, v71
	global_store_dwordx4 v[84:85], v[64:67], off offset:2048 nt
	ds_read_b128 v[64:67], v142 offset:512
	s_waitcnt lgkmcnt(0)
	v_mul_f32_e32 v70, s86, v64
	v_mul_f32_e32 v71, s86, v65
	s_nop 0
	v_mul_f32_e32 v74, v60, v70
	v_mul_f32_e32 v75, v61, v71
	v_mul_f32_e32 v68, s86, v66
	v_mul_f32_e32 v69, s86, v67
	v_exp_f32_e32 v74, v74
	v_exp_f32_e32 v75, v75
	v_mul_f32_e32 v64, v64, v64
	v_mul_f32_e32 v65, v65, v65
	v_mul_f32_e32 v72, v62, v68
	v_mul_f32_e32 v73, v63, v69
	v_mul_f32_e32 v62, v52, v70
	v_mul_f32_e32 v63, v53, v71
	v_add_f32_e32 v74, 1.0, v74
	v_add_f32_e32 v75, 1.0, v75
	v_exp_f32_e32 v62, v62
	v_rcp_f32_e32 v74, v74
	v_rcp_f32_e32 v75, v75
	v_exp_f32_e32 v63, v63
	v_mul_f32_e32 v66, v66, v66
	v_mul_f32_e32 v67, v67, v67
	v_mul_f32_e32 v60, v64, v74
	v_mul_f32_e32 v61, v65, v75
	s_nop 0
	v_mul_f32_e32 v56, v56, v60
	v_mul_f32_e32 v57, v57, v61
	v_exp_f32_e32 v60, v72
	v_exp_f32_e32 v61, v73
	v_add_f32_e32 v62, 1.0, v62
	v_add_f32_e32 v63, 1.0, v63
	v_add_f32_e32 v60, 1.0, v60
	v_add_f32_e32 v61, 1.0, v61
	s_nop 0
	v_rcp_f32_e32 v60, v60
	v_rcp_f32_e32 v61, v61
	v_rcp_f32_e32 v62, v62
	v_rcp_f32_e32 v63, v63
	v_mul_f32_e32 v60, v66, v60
	v_mul_f32_e32 v61, v67, v61
	s_nop 0
	v_mul_f32_e32 v58, v58, v60
	v_mul_f32_e32 v59, v59, v61
	v_mul_f32_e32 v52, v64, v62
	v_mul_f32_e32 v53, v65, v63
	v_mul_f32_e32 v60, v54, v68
	v_mul_f32_e32 v61, v55, v69
	v_mul_f32_e32 v48, v48, v52
	v_mul_f32_e32 v49, v49, v53
	ds_write2_b32 v120, v56, v48 offset1:16
	ds_write2_b32 v121, v57, v49 offset0:36 offset1:52
	v_exp_f32_e32 v48, v60
	v_exp_f32_e32 v49, v61
	s_nop 0
	v_add_f32_e32 v48, 1.0, v48
	v_add_f32_e32 v49, 1.0, v49
	s_nop 0
	v_rcp_f32_e32 v48, v48
	v_rcp_f32_e32 v49, v49
	s_nop 0
	v_mul_f32_e32 v48, v66, v48
	v_mul_f32_e32 v49, v67, v49
	s_nop 0
	v_mul_f32_e32 v48, v50, v48
	v_mul_f32_e32 v49, v51, v49
	ds_write2_b32 v120, v58, v48 offset0:72 offset1:88
	ds_write2_b32 v121, v59, v49 offset0:108 offset1:124
	ds_read_b128 v[48:51], v141
	ds_read_b128 v[52:55], v141 offset:16
	s_waitcnt lgkmcnt(1)
	v_cvt_pk_bf16_f32 v56, v48, v49
	v_cvt_pk_bf16_f32 v57, v50, v51
	s_waitcnt lgkmcnt(0)
	v_cvt_pk_bf16_f32 v58, v52, v53
	v_cvt_pk_bf16_f32 v59, v54, v55
	ds_read_b128 v[52:55], v142 offset:576
	v_add_co_u32_e32 v50, vcc, s0, v128
	s_mov_b32 s0, 0xb1000
	s_nop 0
	v_addc_co_u32_e32 v51, vcc, 0, v129, vcc
	v_add_co_u32_e32 v48, vcc, s0, v128
	s_nop 1
	v_addc_co_u32_e32 v49, vcc, 0, v129, vcc
	global_store_dwordx4 v[48:49], v[56:59], off offset:-4096 nt
	s_waitcnt lgkmcnt(0)
	s_nop 0
	v_mul_f32_e32 v58, s86, v52
	v_mul_f32_e32 v59, s86, v53
	v_mul_f32_e32 v56, s86, v54
	v_mul_f32_e32 v57, s86, v55
	v_mul_f32_e32 v62, v44, v58
	v_mul_f32_e32 v63, v45, v59
	v_mul_f32_e32 v52, v52, v52
	v_mul_f32_e32 v53, v53, v53
	v_exp_f32_e32 v62, v62
	v_exp_f32_e32 v63, v63
	v_mul_f32_e32 v60, v46, v56
	v_mul_f32_e32 v61, v47, v57
	v_mul_f32_e32 v46, v36, v58
	v_mul_f32_e32 v47, v37, v59
	v_mul_f32_e32 v54, v54, v54
	v_mul_f32_e32 v55, v55, v55
	v_add_f32_e32 v62, 1.0, v62
	v_add_f32_e32 v63, 1.0, v63
	v_exp_f32_e32 v46, v46
	v_rcp_f32_e32 v62, v62
	v_rcp_f32_e32 v63, v63
	v_exp_f32_e32 v47, v47
	v_mul_f32_e32 v44, v52, v62
	v_mul_f32_e32 v45, v53, v63
	s_nop 0
	v_mul_f32_e32 v40, v40, v44
	v_mul_f32_e32 v41, v41, v45
	v_exp_f32_e32 v44, v60
	v_exp_f32_e32 v45, v61
	v_add_f32_e32 v46, 1.0, v46
	v_add_f32_e32 v47, 1.0, v47
	v_add_f32_e32 v44, 1.0, v44
	v_add_f32_e32 v45, 1.0, v45
	s_nop 0
	v_rcp_f32_e32 v44, v44
	v_rcp_f32_e32 v45, v45
	v_rcp_f32_e32 v46, v46
	v_rcp_f32_e32 v47, v47
	v_mul_f32_e32 v44, v54, v44
	v_mul_f32_e32 v45, v55, v45
	s_nop 0
	v_mul_f32_e32 v42, v42, v44
	v_mul_f32_e32 v43, v43, v45
	v_mul_f32_e32 v36, v52, v46
	v_mul_f32_e32 v37, v53, v47
	v_mul_f32_e32 v44, v38, v56
	v_mul_f32_e32 v45, v39, v57
	v_mul_f32_e32 v32, v32, v36
	v_mul_f32_e32 v33, v33, v37
	ds_write2_b32 v120, v40, v32 offset1:16
	ds_write2_b32 v121, v41, v33 offset0:36 offset1:52
	v_exp_f32_e32 v32, v44
	v_exp_f32_e32 v33, v45
	s_nop 0
	v_add_f32_e32 v32, 1.0, v32
	v_add_f32_e32 v33, 1.0, v33
	s_nop 0
	v_rcp_f32_e32 v32, v32
	v_rcp_f32_e32 v33, v33
	s_nop 0
	v_mul_f32_e32 v32, v54, v32
	v_mul_f32_e32 v33, v55, v33
	s_nop 0
	v_mul_f32_e32 v32, v34, v32
	v_mul_f32_e32 v33, v35, v33
	ds_write2_b32 v120, v42, v32 offset0:72 offset1:88
	ds_write2_b32 v121, v43, v33 offset0:108 offset1:124
	ds_read_b128 v[32:35], v141
	ds_read_b128 v[36:39], v141 offset:16
	s_waitcnt lgkmcnt(1)
; __device__ __forceinline__ unsigned pack2(float lo, float hi) { unsigned r; asm volatile("v_cvt_pk_bf16_f32 %0, %1, %2" : "=v"(r) : "v"(lo), "v"(hi)); return r; }
; template <int EPI>
; __device__ __forceinline__ void gemm_phase(const GemmDesc d, u16* shm, unsigned sx, unsigned srank, unsigned snloc) {
;     ...
;             const f32x4 r4 = *(const f32x4*)&lr[ai * 128 + wr2 * 64 + m * 16 + fq2 * 4];
;             const f32x4 rc4 = r4 * (-1.4426950408889634f), rr4 = r4 * r4;
; #pragma unroll
;             for (int n = 0; n < 2; ++n)
; #pragma unroll
;               for (int jp = 0; jp < 4; jp += 2) {
;                 const f32x2 a = {acc[ai][0][m][n][jp], acc[ai][0][m][n][jp + 1]}, b = {acc[ai][1][m][n][jp], acc[ai][1][m][n][jp + 1]};
;                 const f32x2 rc = {rc4[jp], rc4[jp + 1]}, rr = {rr4[jp], rr4[jp + 1]};
;                 const f32x2 tl = a * rc;
;                 f32x2 dd = {__builtin_amdgcn_exp2f(tl[0]), __builtin_amdgcn_exp2f(tl[1])};
;                 dd = dd + 1.0f;
;                 const f32x2 s = {__builtin_amdgcn_rcpf(dd[0]), __builtin_amdgcn_rcpf(dd[1])};
;                 const f32x2 o = (a * b) * (rr * s);
;                 stg[(fq2 * 4 + jp) * 36 + n * 16 + fr2] = o[0];
;                 stg[(fq2 * 4 + jp + 1) * 36 + n * 16 + fr2] = o[1];
;               }
;             {
;               const f32x4 v0 = *(const f32x4*)&stg[sw_row * 36 + sw_c8], v1 = *(const f32x4*)&stg[sw_row * 36 + sw_c8 + 4];
;               u32x4 w = {pack2(v0[0], v0[1]), pack2(v0[2], v0[3]), pack2(v1[0], v1[1]), pack2(v1[2], v1[3])};
;               __builtin_nontemporal_store(w, (u32x4*)(sw_base + (size_t)ai * (44 * 8192) + m * 1024));
;             }
;     ...
;       if constexpr (NEED_R) {
;         if (has_next && t2 < 256) lds_r[((it + 1) & 1) * 256 + t2] = R_ZERO(pnn, t2) ? 0.f : rsqrtf(ssn * (1.0f / DM) + EPS);
;       }
	v_cvt_pk_bf16_f32 v32, v32, v33
	v_cvt_pk_bf16_f32 v33, v34, v35
	s_waitcnt lgkmcnt(0)
	v_cvt_pk_bf16_f32 v34, v36, v37
	v_cvt_pk_bf16_f32 v35, v38, v39
	global_store_dwordx4 v[50:51], v[32:35], off offset:2048 nt
	ds_read_b128 v[32:35], v142 offset:640
	s_waitcnt lgkmcnt(0)
	v_mul_f32_e32 v38, s86, v32
	v_mul_f32_e32 v39, s86, v33
	s_nop 0
	v_mul_f32_e32 v42, v28, v38
	v_mul_f32_e32 v43, v29, v39
	v_mul_f32_e32 v36, s86, v34
	v_mul_f32_e32 v37, s86, v35
	v_exp_f32_e32 v42, v42
	v_exp_f32_e32 v43, v43
	v_mul_f32_e32 v32, v32, v32
	v_mul_f32_e32 v33, v33, v33
	v_mul_f32_e32 v40, v30, v36
	v_mul_f32_e32 v41, v31, v37
	v_mul_f32_e32 v30, v20, v38
	v_mul_f32_e32 v31, v21, v39
	v_add_f32_e32 v42, 1.0, v42
	v_add_f32_e32 v43, 1.0, v43
	v_exp_f32_e32 v30, v30
	v_rcp_f32_e32 v42, v42
	v_rcp_f32_e32 v43, v43
	v_exp_f32_e32 v31, v31
	v_mul_f32_e32 v34, v34, v34
	v_mul_f32_e32 v35, v35, v35
	v_mul_f32_e32 v28, v32, v42
	v_mul_f32_e32 v29, v33, v43
	s_nop 0
	v_mul_f32_e32 v24, v24, v28
	v_mul_f32_e32 v25, v25, v29
	v_exp_f32_e32 v28, v40
	v_exp_f32_e32 v29, v41
	v_add_f32_e32 v30, 1.0, v30
	v_add_f32_e32 v31, 1.0, v31
	v_add_f32_e32 v28, 1.0, v28
	v_add_f32_e32 v29, 1.0, v29
	s_nop 0
	v_rcp_f32_e32 v28, v28
	v_rcp_f32_e32 v29, v29
	v_rcp_f32_e32 v30, v30
	v_rcp_f32_e32 v31, v31
	v_mul_f32_e32 v28, v34, v28
	v_mul_f32_e32 v29, v35, v29
	s_nop 0
	v_mul_f32_e32 v26, v26, v28
	v_mul_f32_e32 v27, v27, v29
	v_mul_f32_e32 v20, v32, v30
	v_mul_f32_e32 v21, v33, v31
	v_mul_f32_e32 v28, v22, v36
	v_mul_f32_e32 v29, v23, v37
	v_mul_f32_e32 v16, v16, v20
	v_mul_f32_e32 v17, v17, v21
	ds_write2_b32 v120, v24, v16 offset1:16
	ds_write2_b32 v121, v25, v17 offset0:36 offset1:52
	v_exp_f32_e32 v16, v28
	v_exp_f32_e32 v17, v29
	s_nop 0
	v_add_f32_e32 v16, 1.0, v16
	v_add_f32_e32 v17, 1.0, v17
	s_nop 0
	v_rcp_f32_e32 v16, v16
	v_rcp_f32_e32 v17, v17
	s_nop 0
	v_mul_f32_e32 v16, v34, v16
	v_mul_f32_e32 v17, v35, v17
	s_nop 0
	v_mul_f32_e32 v16, v18, v16
	v_mul_f32_e32 v17, v19, v17
	ds_write2_b32 v120, v26, v16 offset0:72 offset1:88
	ds_write2_b32 v121, v27, v17 offset0:108 offset1:124
	ds_read_b128 v[16:19], v141
	ds_read_b128 v[20:23], v141 offset:16
	s_waitcnt lgkmcnt(1)
	v_cvt_pk_bf16_f32 v16, v16, v17
	v_cvt_pk_bf16_f32 v17, v18, v19
	s_waitcnt lgkmcnt(0)
	v_cvt_pk_bf16_f32 v18, v20, v21
	v_cvt_pk_bf16_f32 v19, v22, v23
	global_store_dwordx4 v[48:49], v[16:19], off nt
	ds_read_b128 v[16:19], v142 offset:704
	s_waitcnt lgkmcnt(0)
	v_mul_f32_e32 v22, s86, v16
	v_mul_f32_e32 v23, s86, v17
	s_nop 0
	v_mul_f32_e32 v26, v12, v22
	v_mul_f32_e32 v27, v13, v23
	v_mul_f32_e32 v20, s86, v18
	v_mul_f32_e32 v21, s86, v19
	v_exp_f32_e32 v26, v26
	v_exp_f32_e32 v27, v27
	v_mul_f32_e32 v16, v16, v16
	v_mul_f32_e32 v17, v17, v17
	v_mul_f32_e32 v24, v14, v20
	v_mul_f32_e32 v25, v15, v21
	v_mul_f32_e32 v14, v4, v22
	v_mul_f32_e32 v15, v5, v23
	v_add_f32_e32 v26, 1.0, v26
	v_add_f32_e32 v27, 1.0, v27
	v_exp_f32_e32 v14, v14
	v_rcp_f32_e32 v26, v26
	v_rcp_f32_e32 v27, v27
	v_exp_f32_e32 v15, v15
	v_mul_f32_e32 v18, v18, v18
	v_mul_f32_e32 v19, v19, v19
	v_mul_f32_e32 v12, v16, v26
	v_mul_f32_e32 v13, v17, v27
	s_nop 0
	v_mul_f32_e32 v8, v8, v12
	v_mul_f32_e32 v9, v9, v13
	v_exp_f32_e32 v12, v24
	v_exp_f32_e32 v13, v25
	v_add_f32_e32 v14, 1.0, v14
	v_add_f32_e32 v15, 1.0, v15
	v_add_f32_e32 v12, 1.0, v12
	v_add_f32_e32 v13, 1.0, v13
	s_nop 0
	v_rcp_f32_e32 v12, v12
	v_rcp_f32_e32 v13, v13
	v_rcp_f32_e32 v14, v14
	v_rcp_f32_e32 v15, v15
	v_mul_f32_e32 v12, v18, v12
	v_mul_f32_e32 v13, v19, v13
	s_nop 0
	v_mul_f32_e32 v10, v10, v12
	v_mul_f32_e32 v11, v11, v13
	v_mul_f32_e32 v4, v16, v14
	v_mul_f32_e32 v5, v17, v15
	v_mul_f32_e32 v12, v6, v20
	v_mul_f32_e32 v13, v7, v21
	v_mul_f32_e32 v0, v0, v4
	v_mul_f32_e32 v1, v1, v5
	ds_write2_b32 v120, v8, v0 offset1:16
	ds_write2_b32 v121, v9, v1 offset0:36 offset1:52
	v_exp_f32_e32 v0, v12
	v_exp_f32_e32 v1, v13
	s_nop 0
	v_add_f32_e32 v0, 1.0, v0
	v_add_f32_e32 v1, 1.0, v1
	s_nop 0
	v_rcp_f32_e32 v0, v0
	v_rcp_f32_e32 v1, v1
	s_nop 0
	v_mul_f32_e32 v0, v18, v0
	v_mul_f32_e32 v1, v19, v1
	s_nop 0
	v_mul_f32_e32 v0, v2, v0
	v_mul_f32_e32 v1, v3, v1
	ds_write2_b32 v120, v10, v0 offset0:72 offset1:88
	ds_write2_b32 v121, v11, v1 offset0:108 offset1:124
	ds_read_b128 v[0:3], v141
	ds_read_b128 v[4:7], v141 offset:16
	s_waitcnt lgkmcnt(1)
	v_cvt_pk_bf16_f32 v0, v0, v1
	v_cvt_pk_bf16_f32 v1, v2, v3
	s_waitcnt lgkmcnt(0)
	v_cvt_pk_bf16_f32 v2, v4, v5
	v_cvt_pk_bf16_f32 v3, v6, v7
	global_store_dwordx4 v[48:49], v[0:3], off offset:2048 nt
	s_and_saveexec_b64 s[4:5], s[34:35]
	s_cbranch_execz .LBB0_1454
	v_cmp_gt_f32_e32 vcc, s31, v140
	v_mul_f32_e32 v0, 0x4b800000, v140
	s_xor_b32 s0, s18, 0x100
	v_cndmask_b32_e32 v0, v140, v0, vcc
	v_rsq_f32_e32 v0, v0
	s_lshl_b32 s0, s0, 2
	s_add_i32 s0, s0, 0
	v_mul_f32_e32 v1, 0x45800000, v0
	v_cndmask_b32_e32 v0, v0, v1, vcc
	v_lshl_add_u32 v1, v139, 2, s0
	v_add_u32_e32 v1, 0x20000, v1
	ds_write_b32 v1, v0
